# GEMM K-loop head pinned with .p2align 6 plus pad nops at byte phase 32 mod 64 (same phase as before, one cache line later); no other change
# speedup vs baseline: 1.0072x; 1.0004x over previous
; #define PG8_STAGE(bufoff, gbase, voff) do { _Pragma("unroll") for (int _i = 0; _i < 2; ++_i) \
;         __builtin_amdgcn_global_load_lds((const unsigned*)((const char*)(gbase) + (voff)[_i]), (LAS unsigned*)(lds + (bufoff) + ldsw + _i * 8192), 16, 0, 0); } while (0)
; #define PG8_LDA(dst, b, h) do { _Pragma("unroll") for (int m = 0; m < 4; ++m) _Pragma("unroll") for (int k = 0; k < 2; ++k) dst[m][k] = *(const LAS bf16x8*)(lds + PG8_SA(b, h) + aoff + m * 2048 + k * 1024); } while (0)
; #define PG8_LDB(dst, b, h) do { _Pragma("unroll") for (int n = 0; n < 2; ++n) _Pragma("unroll") for (int k = 0; k < 2; ++k) dst[n][k] = *(const LAS bf16x8*)(lds + PG8_SB(b, h) + boff + n * 2048 + k * 1024); } while (0)
; #define PG8_MMA(ai, bj, At, Bt) do { __builtin_amdgcn_s_setprio(1); _Pragma("unroll") for (int m = 0; m < 4; ++m) _Pragma("unroll") for (int n = 0; n < 2; ++n) _Pragma("unroll") for (int k = 0; k < 2; ++k) \
;         acc[ai][bj][m][n] = __builtin_amdgcn_mfma_f32_16x16x32_bf16(Bt[n][k], At[m][k], acc[ai][bj][m][n], 0, 0, 0); __builtin_amdgcn_s_setprio(0); } while (0)
; #define PG8_WAIT_V(n) asm volatile("s_waitcnt vmcnt(" #n ")" ::: "memory")
; #define PG8_BAR __builtin_amdgcn_s_barrier()
; __device__ __forceinline__ void gemm_phase(LAS unsigned char* lds, const GemmP g, const EpiP e) {
;     ...
;     for (;;) {
;         const bool has_next = unit_next(g, ui + 1, nxt);
;         const char* nA = has_next ? UNIT_A(nxt) : cA; const char* nB = has_next ? UNIT_B(nxt) : cB;
;         const int nt = cur.nt;
;         for (int t = 0; t < nt; t += 2) {
;             const bool last = (t == nt - 2);
;             const char* a1 = cA + (size_t)(t + 1) * kstepA;
;             const char* a2 = last ? nA : cA + (size_t)(t + 2) * kstepA; const char* b2 = last ? nB : cB + (size_t)(t + 2) * kstepB;
;             const char* a3 = a2 + kstepA; const char* b3 = b2 + kstepB;
;             PG8_LDB(B0, 0, 0); PG8_LDB(B1, 0, 1); PG8_SCHED; PG8_LDA(At, 0, 0); PG8_STAGE(PG8_SA(1, 1), a1 + hstepA, voffA);
;             PG8_WAIT_V(8); PG8_WAIT_L(0); PG8_BAR; PG8_MMA(0, 0, At, B0); PG8_MMA(0, 1, At, B1); PG8_BAR; PG8_SCHED;
;             PG8_LDA(At, 0, 1); PG8_STAGE(PG8_SB(0, 0), b2, voffB); PG8_STAGE(PG8_SB(0, 1), b2 + hstepB, voffB); PG8_STAGE(PG8_SA(0, 0), a2, voffA);
;             PG8_WAIT_V(8); PG8_WAIT_L(0); PG8_BAR; PG8_MMA(1, 0, At, B0); PG8_MMA(1, 1, At, B1); PG8_BAR; PG8_SCHED;
.LBB0_392:
	s_cmp_lt_i32 s69, 1
	s_cbranch_scc1 .LBB0_395
	s_add_u32 s24, s78, s90
	s_addc_u32 s25, s79, s7
	s_add_i32 s26, s69, -2
	s_add_u32 s27, s40, 0x100
	s_addc_u32 s28, s41, 0
	s_mov_b64 s[18:19], 0
	s_cmp_eq_u32 s99, 0
	s_cbranch_scc1 .LBB0_394
	s_mov_b32 s99, 0
	s_add_u32 s30, s18, 1
	s_addc_u32 s31, s19, 0
	s_add_u32 s16, s18, 2
	s_addc_u32 s17, s19, 0
	s_lshl_b64 s[20:21], s[16:17], s77
	s_add_u32 s19, s78, s20
	s_addc_u32 s20, s79, s21
	s_cmp_eq_u32 s26, s18
	s_cselect_b32 s21, s51, s20
	s_cselect_b32 s20, s50, s19
	s_cselect_b32 s22, s80, s27
	s_cselect_b32 s23, s81, s28
	s_add_u32 s18, s20, s38
	s_addc_u32 s19, s21, s39
	s_add_i32 s29, 0, 0x10000
	v_add_u32_e32 v96, s29, v179
	s_add_i32 s34, 0, 0x14000
	ds_read_b128 v[132:135], v96
	ds_read_b128 v[136:139], v96 offset:1024
	ds_read_b128 v[160:163], v96 offset:2048
	ds_read_b128 v[164:167], v96 offset:3072
	v_add_u32_e32 v96, s34, v179
	ds_read_b128 v[168:171], v96
	ds_read_b128 v[172:175], v96 offset:1024
	ds_read_b128 v[216:219], v96 offset:2048
	ds_read_b128 v[220:223], v96 offset:3072
	s_lshl_b64 s[30:31], s[30:31], s77
	s_add_u32 s30, s24, s30
	s_addc_u32 s31, s25, s31
	v_lshl_add_u64 v[98:99], s[30:31], 0, v[140:141]
	s_add_i32 m0, s92, 0xc000
	ds_read_b128 v[224:227], v188
	ds_read_b128 v[228:231], v188 offset:1024
	ds_read_b128 v[232:235], v188 offset:2048
	ds_read_b128 v[236:239], v188 offset:3072
	ds_read_b128 v[240:243], v188 offset:4096
	ds_read_b128 v[244:247], v188 offset:5120
	ds_read_b128 v[248:251], v188 offset:6144
	ds_read_b128 v[204:207], v188 offset:7168
	global_load_lds_dwordx4 v[98:99], off
	v_lshl_add_u64 v[98:99], s[30:31], 0, v[142:143]
	s_add_i32 m0, s92, 0xe000
	s_nop 0
	global_load_lds_dwordx4 v[98:99], off
	s_waitcnt vmcnt(24)
	s_waitcnt lgkmcnt(0)
	s_barrier
	s_setprio 1
	s_waitcnt lgkmcnt(0)
	v_mfma_f32_16x16x32_bf16 v[128:131], v[132:135], v[224:227], v[128:131]
	v_mfma_f32_16x16x32_bf16 v[124:127], v[160:163], v[224:227], v[124:127]
	v_mfma_f32_16x16x32_bf16 v[120:123], v[132:135], v[232:235], v[120:123]
	v_mfma_f32_16x16x32_bf16 v[116:119], v[160:163], v[232:235], v[116:119]
	v_mfma_f32_16x16x32_bf16 v[112:115], v[132:135], v[240:243], v[112:115]
	v_mfma_f32_16x16x32_bf16 v[108:111], v[160:163], v[240:243], v[108:111]
	v_mfma_f32_16x16x32_bf16 v[104:107], v[132:135], v[248:251], v[104:107]
	v_mfma_f32_16x16x32_bf16 v[98:101], v[160:163], v[248:251], v[100:103]
	v_mfma_f32_16x16x32_bf16 v[128:131], v[136:139], v[228:231], v[128:131]
	v_mfma_f32_16x16x32_bf16 v[124:127], v[164:167], v[228:231], v[124:127]
	v_mfma_f32_16x16x32_bf16 v[120:123], v[136:139], v[236:239], v[120:123]
	v_mfma_f32_16x16x32_bf16 v[116:119], v[164:167], v[236:239], v[116:119]
	v_mfma_f32_16x16x32_bf16 v[112:115], v[136:139], v[244:247], v[112:115]
	v_mfma_f32_16x16x32_bf16 v[108:111], v[164:167], v[244:247], v[108:111]
	v_mfma_f32_16x16x32_bf16 v[104:107], v[136:139], v[204:207], v[104:107]
	v_mfma_f32_16x16x32_bf16 v[98:101], v[164:167], v[204:207], v[98:101]
	s_setprio 0
	s_setprio 1
	v_mfma_f32_16x16x32_bf16 v[92:95], v[168:171], v[224:227], v[92:95]
	v_mfma_f32_16x16x32_bf16 v[88:91], v[216:219], v[224:227], v[88:91]
	v_mfma_f32_16x16x32_bf16 v[84:87], v[168:171], v[232:235], v[84:87]
	v_mfma_f32_16x16x32_bf16 v[80:83], v[216:219], v[232:235], v[80:83]
	v_mfma_f32_16x16x32_bf16 v[76:79], v[168:171], v[240:243], v[76:79]
	v_mfma_f32_16x16x32_bf16 v[72:75], v[216:219], v[240:243], v[72:75]
	v_mfma_f32_16x16x32_bf16 v[68:71], v[168:171], v[248:251], v[68:71]
	v_mfma_f32_16x16x32_bf16 v[64:67], v[216:219], v[248:251], v[64:67]
	v_mfma_f32_16x16x32_bf16 v[92:95], v[172:175], v[228:231], v[92:95]
	v_mfma_f32_16x16x32_bf16 v[88:91], v[220:223], v[228:231], v[88:91]
	v_mfma_f32_16x16x32_bf16 v[84:87], v[172:175], v[236:239], v[84:87]
	v_mfma_f32_16x16x32_bf16 v[80:83], v[220:223], v[236:239], v[80:83]
	v_mfma_f32_16x16x32_bf16 v[76:79], v[172:175], v[244:247], v[76:79]
	v_mfma_f32_16x16x32_bf16 v[72:75], v[220:223], v[244:247], v[72:75]
	v_mfma_f32_16x16x32_bf16 v[68:71], v[172:175], v[204:207], v[68:71]
	v_mfma_f32_16x16x32_bf16 v[64:67], v[220:223], v[204:207], v[64:67]
	s_setprio 0
	s_barrier
	s_add_i32 s29, s29, s91
	v_lshl_add_u64 v[176:177], s[22:23], 0, v[146:147]
	s_mov_b32 m0, s29
	ds_read_b128 v[204:207], v188 offset:16384
	ds_read_b128 v[224:227], v188 offset:17408
	ds_read_b128 v[228:231], v188 offset:18432
	ds_read_b128 v[232:235], v188 offset:19456
	ds_read_b128 v[236:239], v188 offset:20480
	ds_read_b128 v[240:243], v188 offset:21504
	ds_read_b128 v[244:247], v188 offset:22528
	ds_read_b128 v[248:251], v188 offset:23552
	global_load_lds_dwordx4 v[176:177], off
	s_add_i32 m0, s29, 0x2000
	v_lshl_add_u64 v[210:211], s[22:23], 0, v[144:145]
	s_add_u32 s22, s22, s48
	s_addc_u32 s23, s23, s49
	s_add_i32 s29, s34, s91
	global_load_lds_dwordx4 v[210:211], off
	v_lshl_add_u64 v[212:213], s[22:23], 0, v[146:147]
	s_mov_b32 m0, s29
	v_lshl_add_u64 v[190:191], s[22:23], 0, v[144:145]
	global_load_lds_dwordx4 v[212:213], off
	s_add_i32 m0, s29, 0x2000
	v_lshl_add_u64 v[102:103], s[20:21], 0, v[140:141]
	global_load_lds_dwordx4 v[190:191], off
	s_mov_b32 m0, s92
	s_nop 0
	global_load_lds_dwordx4 v[102:103], off
	v_lshl_add_u64 v[102:103], s[20:21], 0, v[142:143]
	s_mov_b32 m0, s93
	s_nop 0
	global_load_lds_dwordx4 v[102:103], off
	s_waitcnt vmcnt(24)
	s_waitcnt lgkmcnt(0)
	s_barrier
; #define PG8_STAGE(bufoff, gbase, voff) do { _Pragma("unroll") for (int _i = 0; _i < 2; ++_i) \
;         __builtin_amdgcn_global_load_lds((const unsigned*)((const char*)(gbase) + (voff)[_i]), (LAS unsigned*)(lds + (bufoff) + ldsw + _i * 8192), 16, 0, 0); } while (0)
; #define PG8_LDA(dst, b, h) do { _Pragma("unroll") for (int m = 0; m < 4; ++m) _Pragma("unroll") for (int k = 0; k < 2; ++k) dst[m][k] = *(const LAS bf16x8*)(lds + PG8_SA(b, h) + aoff + m * 2048 + k * 1024); } while (0)
; #define PG8_LDB(dst, b, h) do { _Pragma("unroll") for (int n = 0; n < 2; ++n) _Pragma("unroll") for (int k = 0; k < 2; ++k) dst[n][k] = *(const LAS bf16x8*)(lds + PG8_SB(b, h) + boff + n * 2048 + k * 1024); } while (0)
; #define PG8_MMA(ai, bj, At, Bt) do { __builtin_amdgcn_s_setprio(1); _Pragma("unroll") for (int m = 0; m < 4; ++m) _Pragma("unroll") for (int n = 0; n < 2; ++n) _Pragma("unroll") for (int k = 0; k < 2; ++k) \
;         acc[ai][bj][m][n] = __builtin_amdgcn_mfma_f32_16x16x32_bf16(Bt[n][k], At[m][k], acc[ai][bj][m][n], 0, 0, 0); __builtin_amdgcn_s_setprio(0); } while (0)
; #define PG8_WAIT_V(n) asm volatile("s_waitcnt vmcnt(" #n ")" ::: "memory")
; #define PG8_WAIT_L(n) asm volatile("s_waitcnt lgkmcnt(" #n ")" ::: "memory")
; #define PG8_BAR __builtin_amdgcn_s_barrier()
; #define PG8_SCHED __builtin_amdgcn_sched_barrier(0)
; __device__ __forceinline__ void gemm_phase(LAS unsigned char* lds, const GemmP g, const EpiP e) {
;     ...
;             PG8_LDA(At, 0, 1); PG8_STAGE(PG8_SB(0, 0), b2, voffB); PG8_STAGE(PG8_SB(0, 1), b2 + hstepB, voffB); PG8_STAGE(PG8_SA(0, 0), a2, voffA);
;             PG8_WAIT_V(8); PG8_WAIT_L(0); PG8_BAR; PG8_MMA(1, 0, At, B0); PG8_MMA(1, 1, At, B1); PG8_BAR; PG8_SCHED;
;             PG8_LDB(B0, 1, 0); PG8_LDB(B1, 1, 1); PG8_SCHED; PG8_LDA(At, 1, 0); PG8_STAGE(PG8_SA(0, 1), a2 + hstepA, voffA);
;             PG8_WAIT_V(8); PG8_WAIT_L(0); PG8_BAR; PG8_MMA(0, 0, At, B0); PG8_MMA(0, 1, At, B1); PG8_BAR; PG8_SCHED;
	s_setprio 1
	s_waitcnt lgkmcnt(0)
	v_mfma_f32_16x16x32_bf16 v[60:63], v[132:135], v[204:207], v[60:63]
	v_mfma_f32_16x16x32_bf16 v[56:59], v[160:163], v[204:207], v[56:59]
	v_mfma_f32_16x16x32_bf16 v[52:55], v[132:135], v[228:231], v[52:55]
	v_mfma_f32_16x16x32_bf16 v[48:51], v[160:163], v[228:231], v[48:51]
	v_mfma_f32_16x16x32_bf16 v[44:47], v[132:135], v[236:239], v[44:47]
	v_mfma_f32_16x16x32_bf16 v[40:43], v[160:163], v[236:239], v[40:43]
	v_mfma_f32_16x16x32_bf16 v[36:39], v[132:135], v[244:247], v[36:39]
	v_mfma_f32_16x16x32_bf16 v[32:35], v[160:163], v[244:247], v[32:35]
	v_mfma_f32_16x16x32_bf16 v[60:63], v[136:139], v[224:227], v[60:63]
	v_mfma_f32_16x16x32_bf16 v[56:59], v[164:167], v[224:227], v[56:59]
	v_mfma_f32_16x16x32_bf16 v[52:55], v[136:139], v[232:235], v[52:55]
	v_mfma_f32_16x16x32_bf16 v[48:51], v[164:167], v[232:235], v[48:51]
	v_mfma_f32_16x16x32_bf16 v[44:47], v[136:139], v[240:243], v[44:47]
	v_mfma_f32_16x16x32_bf16 v[40:43], v[164:167], v[240:243], v[40:43]
	v_mfma_f32_16x16x32_bf16 v[36:39], v[136:139], v[248:251], v[36:39]
	v_mfma_f32_16x16x32_bf16 v[32:35], v[164:167], v[248:251], v[32:35]
	s_setprio 0
	s_setprio 1
	v_mfma_f32_16x16x32_bf16 v[28:31], v[168:171], v[204:207], v[28:31]
	v_mfma_f32_16x16x32_bf16 v[24:27], v[216:219], v[204:207], v[24:27]
	v_mfma_f32_16x16x32_bf16 v[20:23], v[168:171], v[228:231], v[20:23]
	v_mfma_f32_16x16x32_bf16 v[16:19], v[216:219], v[228:231], v[16:19]
	v_mfma_f32_16x16x32_bf16 v[12:15], v[168:171], v[236:239], v[12:15]
	v_mfma_f32_16x16x32_bf16 v[8:11], v[216:219], v[236:239], v[8:11]
	v_mfma_f32_16x16x32_bf16 v[4:7], v[168:171], v[244:247], v[4:7]
	v_mfma_f32_16x16x32_bf16 v[0:3], v[216:219], v[244:247], v[0:3]
	v_mfma_f32_16x16x32_bf16 v[28:31], v[172:175], v[224:227], v[28:31]
	v_mfma_f32_16x16x32_bf16 v[24:27], v[220:223], v[224:227], v[24:27]
	v_mfma_f32_16x16x32_bf16 v[20:23], v[172:175], v[232:235], v[20:23]
	v_mfma_f32_16x16x32_bf16 v[16:19], v[220:223], v[232:235], v[16:19]
	v_mfma_f32_16x16x32_bf16 v[12:15], v[172:175], v[240:243], v[12:15]
	v_mfma_f32_16x16x32_bf16 v[8:11], v[220:223], v[240:243], v[8:11]
	v_mfma_f32_16x16x32_bf16 v[4:7], v[172:175], v[248:251], v[4:7]
	v_mfma_f32_16x16x32_bf16 v[0:3], v[220:223], v[248:251], v[0:3]
	s_setprio 0
	s_barrier
	s_add_i32 s22, 0, 0x18000
	v_add_u32_e32 v96, s22, v179
	s_add_i32 s23, 0, 0x1c000
	ds_read_b128 v[132:135], v96
	ds_read_b128 v[136:139], v96 offset:1024
	ds_read_b128 v[160:163], v96 offset:2048
	ds_read_b128 v[164:167], v96 offset:3072
	v_add_u32_e32 v96, s23, v179
	ds_read_b128 v[168:171], v96
	ds_read_b128 v[172:175], v96 offset:1024
	ds_read_b128 v[204:207], v96 offset:2048
	ds_read_b128 v[216:219], v96 offset:3072
	s_add_u32 s20, s20, s90
	s_addc_u32 s21, s21, s7
	s_mov_b32 m0, s73
	v_lshl_add_u64 v[102:103], s[20:21], 0, v[140:141]
	ds_read_b128 v[220:223], v188 offset:32768
	ds_read_b128 v[224:227], v188 offset:33792
	ds_read_b128 v[228:231], v188 offset:34816
	ds_read_b128 v[232:235], v188 offset:35840
	ds_read_b128 v[236:239], v188 offset:36864
	ds_read_b128 v[240:243], v188 offset:37888
	ds_read_b128 v[244:247], v188 offset:38912
	ds_read_b128 v[248:251], v188 offset:39936
	global_load_lds_dwordx4 v[102:103], off
	v_lshl_add_u64 v[102:103], s[20:21], 0, v[142:143]
	s_mov_b32 m0, s4
	s_nop 0
	global_load_lds_dwordx4 v[102:103], off
	s_waitcnt vmcnt(8)
	s_waitcnt lgkmcnt(0)
	s_barrier
	s_setprio 1
	s_waitcnt lgkmcnt(0)
	v_mfma_f32_16x16x32_bf16 v[128:131], v[132:135], v[220:223], v[128:131]
	v_mfma_f32_16x16x32_bf16 v[124:127], v[160:163], v[220:223], v[124:127]
	v_mfma_f32_16x16x32_bf16 v[120:123], v[132:135], v[228:231], v[120:123]
	v_mfma_f32_16x16x32_bf16 v[116:119], v[160:163], v[228:231], v[116:119]
	v_mfma_f32_16x16x32_bf16 v[112:115], v[132:135], v[236:239], v[112:115]
	v_mfma_f32_16x16x32_bf16 v[108:111], v[160:163], v[236:239], v[108:111]
	v_mfma_f32_16x16x32_bf16 v[102:105], v[132:135], v[244:247], v[104:107]
	v_mfma_f32_16x16x32_bf16 v[98:101], v[160:163], v[244:247], v[98:101]
	v_mfma_f32_16x16x32_bf16 v[128:131], v[136:139], v[224:227], v[128:131]
	v_mfma_f32_16x16x32_bf16 v[124:127], v[164:167], v[224:227], v[124:127]
	v_mfma_f32_16x16x32_bf16 v[120:123], v[136:139], v[232:235], v[120:123]
	v_mfma_f32_16x16x32_bf16 v[116:119], v[164:167], v[232:235], v[116:119]
	v_mfma_f32_16x16x32_bf16 v[112:115], v[136:139], v[240:243], v[112:115]
	v_mfma_f32_16x16x32_bf16 v[108:111], v[164:167], v[240:243], v[108:111]
	v_mfma_f32_16x16x32_bf16 v[104:107], v[136:139], v[248:251], v[102:105]
	v_mfma_f32_16x16x32_bf16 v[100:103], v[164:167], v[248:251], v[98:101]
	s_setprio 0
	s_setprio 1
	v_mfma_f32_16x16x32_bf16 v[92:95], v[168:171], v[220:223], v[92:95]
	v_mfma_f32_16x16x32_bf16 v[88:91], v[204:207], v[220:223], v[88:91]
	v_mfma_f32_16x16x32_bf16 v[84:87], v[168:171], v[228:231], v[84:87]
	v_mfma_f32_16x16x32_bf16 v[80:83], v[204:207], v[228:231], v[80:83]
	v_mfma_f32_16x16x32_bf16 v[76:79], v[168:171], v[236:239], v[76:79]
	v_mfma_f32_16x16x32_bf16 v[72:75], v[204:207], v[236:239], v[72:75]
	v_mfma_f32_16x16x32_bf16 v[68:71], v[168:171], v[244:247], v[68:71]
	v_mfma_f32_16x16x32_bf16 v[64:67], v[204:207], v[244:247], v[64:67]
	v_mfma_f32_16x16x32_bf16 v[92:95], v[172:175], v[224:227], v[92:95]
	v_mfma_f32_16x16x32_bf16 v[88:91], v[216:219], v[224:227], v[88:91]
	v_mfma_f32_16x16x32_bf16 v[84:87], v[172:175], v[232:235], v[84:87]
	v_mfma_f32_16x16x32_bf16 v[80:83], v[216:219], v[232:235], v[80:83]
	v_mfma_f32_16x16x32_bf16 v[76:79], v[172:175], v[240:243], v[76:79]
	v_mfma_f32_16x16x32_bf16 v[72:75], v[216:219], v[240:243], v[72:75]
	v_mfma_f32_16x16x32_bf16 v[68:71], v[172:175], v[248:251], v[68:71]
	v_mfma_f32_16x16x32_bf16 v[64:67], v[216:219], v[248:251], v[64:67]
	s_setprio 0
	s_barrier
; #define PG8_STAGE(bufoff, gbase, voff) do { _Pragma("unroll") for (int _i = 0; _i < 2; ++_i) \
;         __builtin_amdgcn_global_load_lds((const unsigned*)((const char*)(gbase) + (voff)[_i]), (LAS unsigned*)(lds + (bufoff) + ldsw + _i * 8192), 16, 0, 0); } while (0)
; #define PG8_LDA(dst, b, h) do { _Pragma("unroll") for (int m = 0; m < 4; ++m) _Pragma("unroll") for (int k = 0; k < 2; ++k) dst[m][k] = *(const LAS bf16x8*)(lds + PG8_SA(b, h) + aoff + m * 2048 + k * 1024); } while (0)
; #define PG8_MMA(ai, bj, At, Bt) do { __builtin_amdgcn_s_setprio(1); _Pragma("unroll") for (int m = 0; m < 4; ++m) _Pragma("unroll") for (int n = 0; n < 2; ++n) _Pragma("unroll") for (int k = 0; k < 2; ++k) \
;         acc[ai][bj][m][n] = __builtin_amdgcn_mfma_f32_16x16x32_bf16(Bt[n][k], At[m][k], acc[ai][bj][m][n], 0, 0, 0); __builtin_amdgcn_s_setprio(0); } while (0)
; #define PG8_WAIT_V(n) asm volatile("s_waitcnt vmcnt(" #n ")" ::: "memory")
; #define PG8_WAIT_L(n) asm volatile("s_waitcnt lgkmcnt(" #n ")" ::: "memory")
; #define PG8_BAR __builtin_amdgcn_s_barrier()
; #define PG8_SCHED __builtin_amdgcn_sched_barrier(0)
; __device__ __forceinline__ void gemm_phase(LAS unsigned char* lds, const GemmP g, const EpiP e) {
;     ...
;     for (;;) {
;         const bool has_next = unit_next(g, ui + 1, nxt);
;         const char* nA = has_next ? UNIT_A(nxt) : cA; const char* nB = has_next ? UNIT_B(nxt) : cB;
;         const int nt = cur.nt;
;         for (int t = 0; t < nt; t += 2) {
;             const bool last = (t == nt - 2);
;             const char* a1 = cA + (size_t)(t + 1) * kstepA;
;             const char* a2 = last ? nA : cA + (size_t)(t + 2) * kstepA; const char* b2 = last ? nB : cB + (size_t)(t + 2) * kstepB;
;     ...
;             PG8_LDA(At, 1, 1); PG8_STAGE(PG8_SB(1, 0), b3, voffB); PG8_STAGE(PG8_SB(1, 1), b3 + hstepB, voffB); PG8_STAGE(PG8_SA(1, 0), a3, voffA);
;             PG8_WAIT_V(8); PG8_WAIT_L(0); PG8_BAR; PG8_MMA(1, 0, At, B0); PG8_MMA(1, 1, At, B1); PG8_BAR; PG8_SCHED;
	s_add_i32 s20, s22, s91
	v_lshl_add_u64 v[98:99], v[176:177], 0, s[96:97]
	s_mov_b32 m0, s20
	ds_read_b128 v[220:223], v188 offset:49152
	ds_read_b128 v[224:227], v188 offset:50176
	ds_read_b128 v[228:231], v188 offset:51200
	ds_read_b128 v[232:235], v188 offset:52224
	ds_read_b128 v[236:239], v188 offset:53248
	ds_read_b128 v[240:243], v188 offset:54272
	ds_read_b128 v[244:247], v188 offset:55296
	ds_read_b128 v[248:251], v188 offset:56320
	global_load_lds_dwordx4 v[98:99], off
	v_lshl_add_u64 v[98:99], v[210:211], 0, s[96:97]
	s_add_i32 m0, s20, 0x2000
	s_add_i32 s20, s23, s91
	global_load_lds_dwordx4 v[98:99], off
	v_lshl_add_u64 v[98:99], v[212:213], 0, s[96:97]
	s_mov_b32 m0, s20
	s_nop 0
	global_load_lds_dwordx4 v[98:99], off
	v_lshl_add_u64 v[98:99], v[190:191], 0, s[96:97]
	s_add_i32 m0, s20, 0x2000
	s_nop 0
	global_load_lds_dwordx4 v[98:99], off
	v_lshl_add_u64 v[98:99], s[18:19], 0, v[140:141]
	s_mov_b32 m0, s5
	s_nop 0
	global_load_lds_dwordx4 v[98:99], off
	v_lshl_add_u64 v[98:99], s[18:19], 0, v[142:143]
	s_mov_b32 m0, s44
	s_nop 0
	global_load_lds_dwordx4 v[98:99], off
	s_waitcnt vmcnt(8)
	s_waitcnt lgkmcnt(0)
	s_barrier
	s_setprio 1
	s_waitcnt lgkmcnt(0)
	v_mfma_f32_16x16x32_bf16 v[60:63], v[132:135], v[220:223], v[60:63]
	v_mfma_f32_16x16x32_bf16 v[56:59], v[160:163], v[220:223], v[56:59]
	v_mfma_f32_16x16x32_bf16 v[52:55], v[132:135], v[228:231], v[52:55]
	v_mfma_f32_16x16x32_bf16 v[48:51], v[160:163], v[228:231], v[48:51]
	v_mfma_f32_16x16x32_bf16 v[44:47], v[132:135], v[236:239], v[44:47]
	v_mfma_f32_16x16x32_bf16 v[40:43], v[160:163], v[236:239], v[40:43]
	v_mfma_f32_16x16x32_bf16 v[36:39], v[132:135], v[244:247], v[36:39]
	v_mfma_f32_16x16x32_bf16 v[32:35], v[160:163], v[244:247], v[32:35]
	v_mfma_f32_16x16x32_bf16 v[60:63], v[136:139], v[224:227], v[60:63]
	v_mfma_f32_16x16x32_bf16 v[56:59], v[164:167], v[224:227], v[56:59]
	v_mfma_f32_16x16x32_bf16 v[52:55], v[136:139], v[232:235], v[52:55]
	v_mfma_f32_16x16x32_bf16 v[48:51], v[164:167], v[232:235], v[48:51]
	v_mfma_f32_16x16x32_bf16 v[44:47], v[136:139], v[240:243], v[44:47]
	v_mfma_f32_16x16x32_bf16 v[40:43], v[164:167], v[240:243], v[40:43]
	v_mfma_f32_16x16x32_bf16 v[36:39], v[136:139], v[248:251], v[36:39]
	v_mfma_f32_16x16x32_bf16 v[32:35], v[164:167], v[248:251], v[32:35]
	s_setprio 0
	s_setprio 1
	v_mfma_f32_16x16x32_bf16 v[28:31], v[168:171], v[220:223], v[28:31]
	v_mfma_f32_16x16x32_bf16 v[24:27], v[204:207], v[220:223], v[24:27]
	v_mfma_f32_16x16x32_bf16 v[20:23], v[168:171], v[228:231], v[20:23]
	v_mfma_f32_16x16x32_bf16 v[16:19], v[204:207], v[228:231], v[16:19]
	v_mfma_f32_16x16x32_bf16 v[12:15], v[168:171], v[236:239], v[12:15]
	v_mfma_f32_16x16x32_bf16 v[8:11], v[204:207], v[236:239], v[8:11]
	v_mfma_f32_16x16x32_bf16 v[4:7], v[168:171], v[244:247], v[4:7]
	v_mfma_f32_16x16x32_bf16 v[0:3], v[204:207], v[244:247], v[0:3]
	v_mfma_f32_16x16x32_bf16 v[28:31], v[172:175], v[224:227], v[28:31]
	v_mfma_f32_16x16x32_bf16 v[24:27], v[216:219], v[224:227], v[24:27]
	v_mfma_f32_16x16x32_bf16 v[20:23], v[172:175], v[232:235], v[20:23]
	v_mfma_f32_16x16x32_bf16 v[16:19], v[216:219], v[232:235], v[16:19]
	v_mfma_f32_16x16x32_bf16 v[12:15], v[172:175], v[240:243], v[12:15]
	v_mfma_f32_16x16x32_bf16 v[8:11], v[216:219], v[240:243], v[8:11]
	v_mfma_f32_16x16x32_bf16 v[4:7], v[172:175], v[248:251], v[4:7]
	v_mfma_f32_16x16x32_bf16 v[0:3], v[216:219], v[248:251], v[0:3]
	s_setprio 0
	s_barrier
	s_add_u32 s27, s27, 0x100
	s_addc_u32 s28, s28, 0
	s_cmp_ge_i32 s16, s69
	s_mov_b64 s[18:19], s[16:17]
	s_cbranch_scc0 .LBB0_394
	s_branch .LBB0_395
	.p2align 6
	s_nop 0
	s_nop 0
	s_nop 0
	s_nop 0
	s_nop 0
	s_nop 0
	s_nop 0
	s_nop 0
